# prep phases: the 160 one-shot f32 weight loads of the conversion loops marked non-temporal so they do not displace activations from the caches
# speedup vs baseline: 1.0072x; 1.0072x over previous
; DI void conv_item(const float* W, int K, int N, bf16_t* WT, int mode, float* scr, int item, int lane) {
;     const int nblk = (N + 31) / 32, kb = item / nblk, nb = item % nblk, k0 = 64 * kb, n0 = 32 * nb;
;     const int nn = n0 + (lane & 31); const bool okn = nn < N;
;     float wv[32];
; #pragma unroll
;     for (int i = 0; i < 32; ++i) { const int kk = 2 * i + (lane >> 5); wv[i] = okn ? W[(size_t)(k0 + kk) * N + nn] : 0.f; }
; #pragma unroll
;     for (int i = 0; i < 32; ++i) { const int kk = 2 * i + (lane >> 5); scr[kk * 33 + (lane & 31)] = wv[i]; }
.LBB0_797:
	v_cmp_lt_i32_e32 vcc, s31, v29
	v_add_u32_e32 v15, 0x400, v21
	v_add_u32_e32 v14, 0x800, v21
	v_add_u32_e32 v13, 0xc00, v21
	v_add_u32_e32 v12, 0x1000, v21
	v_add_u32_e32 v11, 0x1400, v21
	v_add_u32_e32 v10, 0x1800, v21
	v_add_u32_e32 v7, 0x1c00, v21
	s_and_saveexec_b64 s[4:5], vcc
	s_xor_b64 s[22:23], exec, s[4:5]
	s_cbranch_execz .LBB0_799
	v_and_b32_e32 v42, 0x3e0, v27
	v_and_b32_e32 v6, 0x1ffc0, v28
	v_or_b32_e32 v8, v42, v5
	v_or_b32_e32 v16, v6, v20
	v_lshlrev_b32_e32 v164, 2, v8
	v_lshl_add_u64 v[8:9], s[14:15], 0, v[164:165]
	v_lshlrev_b32_e32 v164, 12, v16
	v_lshl_add_u64 v[8:9], v[8:9], 0, v[164:165]
	v_add_co_u32_e32 v16, vcc, 0x2000, v8
	s_mov_b32 s4, 0x10000
	s_nop 0
	v_addc_co_u32_e32 v17, vcc, 0, v9, vcc
	v_add_co_u32_e32 v18, vcc, 0x4000, v8
	v_lshlrev_b32_e32 v164, 1, v6
	s_nop 0
	v_addc_co_u32_e32 v19, vcc, 0, v9, vcc
	v_add_co_u32_e32 v30, vcc, 0x6000, v8
	s_nop 1
	v_addc_co_u32_e32 v31, vcc, 0, v9, vcc
	v_add_co_u32_e32 v32, vcc, 0x8000, v8
	s_nop 1
	v_addc_co_u32_e32 v33, vcc, 0, v9, vcc
	v_add_co_u32_e32 v34, vcc, 0xa000, v8
	s_nop 1
	v_addc_co_u32_e32 v35, vcc, 0, v9, vcc
	v_add_co_u32_e32 v36, vcc, 0xc000, v8
	s_nop 1
	v_addc_co_u32_e32 v37, vcc, 0, v9, vcc
	v_add_co_u32_e32 v38, vcc, 0xe000, v8
	s_nop 1
	v_addc_co_u32_e32 v39, vcc, 0, v9, vcc
	global_load_dword v43, v[8:9], off nt
	global_load_dword v44, v[16:17], off nt
	global_load_dword v45, v[18:19], off nt
	global_load_dword v46, v[30:31], off nt
	global_load_dword v47, v[32:33], off nt
	global_load_dword v48, v[34:35], off nt
	global_load_dword v49, v[36:37], off nt
	global_load_dword v50, v[38:39], off nt
	v_add_co_u32_e32 v16, vcc, s4, v8
	s_mov_b32 s4, 0x14000
	s_nop 0
	v_addc_co_u32_e32 v17, vcc, 0, v9, vcc
	v_add_co_u32_e32 v18, vcc, 0x12000, v8
	s_nop 1
	v_addc_co_u32_e32 v19, vcc, 0, v9, vcc
	v_add_co_u32_e32 v30, vcc, s4, v8
	s_mov_b32 s4, 0x18000
	s_nop 0
	v_addc_co_u32_e32 v31, vcc, 0, v9, vcc
	v_add_co_u32_e32 v32, vcc, 0x16000, v8
	s_nop 1
	v_addc_co_u32_e32 v33, vcc, 0, v9, vcc
	v_add_co_u32_e32 v34, vcc, s4, v8
	s_mov_b32 s4, 0x1c000
	s_nop 0
	v_addc_co_u32_e32 v35, vcc, 0, v9, vcc
	v_add_co_u32_e32 v36, vcc, 0x1a000, v8
	s_nop 1
	v_addc_co_u32_e32 v37, vcc, 0, v9, vcc
	v_add_co_u32_e32 v38, vcc, s4, v8
	s_mov_b32 s4, 0x30000
	s_nop 0
	v_addc_co_u32_e32 v39, vcc, 0, v9, vcc
	v_add_co_u32_e32 v40, vcc, 0x1e000, v8
	s_nop 1
	v_addc_co_u32_e32 v41, vcc, 0, v9, vcc
	global_load_dword v51, v[16:17], off nt
	global_load_dword v52, v[18:19], off nt
	global_load_dword v53, v[30:31], off nt
	global_load_dword v54, v[32:33], off nt
	global_load_dword v55, v[34:35], off nt
	global_load_dword v56, v[36:37], off nt
	global_load_dword v57, v[38:39], off nt
	global_load_dword v58, v[40:41], off nt
	v_add_co_u32_e32 v16, vcc, 0x20000, v8
	s_nop 1
	v_addc_co_u32_e32 v17, vcc, 0, v9, vcc
	v_add_co_u32_e32 v18, vcc, 0x22000, v8
	s_nop 1
	v_addc_co_u32_e32 v19, vcc, 0, v9, vcc
	v_add_co_u32_e32 v30, vcc, 0x24000, v8
	s_nop 1
	v_addc_co_u32_e32 v31, vcc, 0, v9, vcc
	v_add_co_u32_e32 v32, vcc, 0x26000, v8
	s_nop 1
	v_addc_co_u32_e32 v33, vcc, 0, v9, vcc
	v_add_co_u32_e32 v34, vcc, 0x28000, v8
	s_nop 1
	v_addc_co_u32_e32 v35, vcc, 0, v9, vcc
	v_add_co_u32_e32 v36, vcc, 0x2a000, v8
	s_nop 1
	v_addc_co_u32_e32 v37, vcc, 0, v9, vcc
	v_add_co_u32_e32 v38, vcc, 0x2c000, v8
	s_nop 1
	v_addc_co_u32_e32 v39, vcc, 0, v9, vcc
	v_add_co_u32_e32 v40, vcc, 0x2e000, v8
	s_nop 1
	v_addc_co_u32_e32 v41, vcc, 0, v9, vcc
	global_load_dword v59, v[16:17], off nt
	global_load_dword v60, v[18:19], off nt
	global_load_dword v61, v[30:31], off nt
	global_load_dword v62, v[32:33], off nt
	global_load_dword v63, v[34:35], off nt
	global_load_dword v65, v[36:37], off nt
	global_load_dword v66, v[38:39], off nt
	s_nop 0
	global_load_dword v40, v[40:41], off nt
	v_add_co_u32_e32 v16, vcc, s4, v8
	s_nop 1
	v_addc_co_u32_e32 v17, vcc, 0, v9, vcc
	v_add_co_u32_e32 v18, vcc, 0x32000, v8
	s_nop 1
	v_addc_co_u32_e32 v19, vcc, 0, v9, vcc
	v_add_co_u32_e32 v30, vcc, 0x34000, v8
	s_nop 1
	v_addc_co_u32_e32 v31, vcc, 0, v9, vcc
	v_add_co_u32_e32 v32, vcc, 0x36000, v8
	s_nop 1
	v_addc_co_u32_e32 v33, vcc, 0, v9, vcc
	v_add_co_u32_e32 v34, vcc, 0x38000, v8
	s_nop 1
	v_addc_co_u32_e32 v35, vcc, 0, v9, vcc
	v_add_co_u32_e32 v36, vcc, 0x3a000, v8
	s_nop 1
	v_addc_co_u32_e32 v37, vcc, 0, v9, vcc
	v_add_co_u32_e32 v38, vcc, 0x3c000, v8
	s_nop 1
	v_addc_co_u32_e32 v39, vcc, 0, v9, vcc
	v_add_co_u32_e32 v8, vcc, 0x3e000, v8
	s_nop 1
	v_addc_co_u32_e32 v9, vcc, 0, v9, vcc
	global_load_dword v16, v[16:17], off nt
	s_nop 0
	global_load_dword v17, v[18:19], off nt
	s_nop 0
	global_load_dword v18, v[30:31], off nt
	global_load_dword v19, v[32:33], off nt
	s_nop 0
	global_load_dword v30, v[34:35], off nt
	global_load_dword v31, v[36:37], off nt
	global_load_dword v32, v[38:39], off nt
	s_nop 0
	global_load_dword v8, v[8:9], off nt
	s_waitcnt vmcnt(30)
	ds_write2_b32 v21, v43, v44 offset1:66
	s_waitcnt vmcnt(28)
	ds_write2_b32 v21, v45, v46 offset0:132 offset1:198
	s_waitcnt vmcnt(26)
	ds_write2_b32 v15, v47, v48 offset0:8 offset1:74
	s_waitcnt vmcnt(24)
	ds_write2_b32 v15, v49, v50 offset0:140 offset1:206
	s_waitcnt vmcnt(22)
	ds_write2_b32 v14, v51, v52 offset0:16 offset1:82
	s_waitcnt vmcnt(20)
	ds_write2_b32 v14, v53, v54 offset0:148 offset1:214
	s_waitcnt vmcnt(18)
	ds_write2_b32 v13, v55, v56 offset0:24 offset1:90
	s_waitcnt vmcnt(16)
	ds_write2_b32 v13, v57, v58 offset0:156 offset1:222
	s_waitcnt vmcnt(14)
	ds_write2_b32 v12, v59, v60 offset0:32 offset1:98
	s_waitcnt vmcnt(12)
	ds_write2_b32 v12, v61, v62 offset0:164 offset1:230
	s_waitcnt vmcnt(10)
	ds_write2_b32 v11, v63, v65 offset0:40 offset1:106
	s_waitcnt vmcnt(8)
; DI unsigned pk2(float lo, float hi) { f32x2_t v = {lo, hi}; bf16x2_t b = __builtin_convertvector(v, bf16x2_t); return __builtin_bit_cast(unsigned, b); }
; DI void conv_item(const float* W, int K, int N, bf16_t* WT, int mode, float* scr, int item, int lane) {
;     const int nblk = (N + 31) / 32, kb = item / nblk, nb = item % nblk, k0 = 64 * kb, n0 = 32 * nb;
;     const int nn = n0 + (lane & 31); const bool okn = nn < N;
;     float wv[32];
; #pragma unroll
;     for (int i = 0; i < 32; ++i) { const int kk = 2 * i + (lane >> 5); wv[i] = okn ? W[(size_t)(k0 + kk) * N + nn] : 0.f; }
;     ...
;     for (int i = 0; i < 32; ++i) { const int kk = 2 * i + (lane >> 5); scr[kk * 33 + (lane & 31)] = wv[i]; }
;     asm volatile("s_waitcnt lgkmcnt(0)" ::: "memory");
;     const int c = lane & 7;
; #pragma unroll
;     for (int j = 0; j < 4; ++j) { const int n = (lane >> 3) + 8 * j; const float* s = scr + (8 * c) * 33 + n;
;         u32x4 o; o.x = pk2(s[0 * 33], s[1 * 33]); o.y = pk2(s[2 * 33], s[3 * 33]); o.z = pk2(s[4 * 33], s[5 * 33]); o.w = pk2(s[6 * 33], s[7 * 33]);
;         if (n0 + n < N) *(u32x4*)(WT + (size_t)dstrow(mode, n0 + n) * K + k0 + 8 * c) = o; }
;     asm volatile("s_waitcnt lgkmcnt(0)" ::: "memory");
; }
	ds_write2_b32 v11, v66, v40 offset0:172 offset1:238
	s_waitcnt vmcnt(6)
	ds_write2_b32 v10, v16, v17 offset0:48 offset1:114
	s_waitcnt vmcnt(4)
	ds_write2_b32 v10, v18, v19 offset0:180 offset1:246
	s_waitcnt vmcnt(2)
	ds_write2_b32 v7, v30, v31 offset0:56 offset1:122
	s_waitcnt vmcnt(0)
	ds_write2_b32 v7, v32, v8 offset0:188 offset1:254
	s_waitcnt lgkmcnt(0)
	ds_read2_b32 v[12:13], v23 offset0:198 offset1:206
	ds_read2_b32 v[14:15], v23 offset0:231 offset1:239
	ds_read2_b32 v[16:17], v23 offset0:132 offset1:140
	ds_read2_b32 v[18:19], v23 offset0:165 offset1:173
	ds_read2_b32 v[30:31], v23 offset0:66 offset1:74
	ds_read2_b32 v[32:33], v23 offset0:99 offset1:107
	ds_read2_b32 v[34:35], v23 offset0:33 offset1:41
	ds_read2_b32 v[36:37], v23 offset1:8
	v_or_b32_e32 v38, v42, v22
	s_waitcnt lgkmcnt(6)
	v_cvt_pk_bf16_f32 v9, v12, v14
	v_mul_u32_u24_e32 v12, 0xb00, v38
	v_lshl_add_u64 v[10:11], v[0:1], 0, v[164:165]
	v_lshlrev_b32_e32 v164, 1, v12
	v_or_b32_e32 v12, v42, v24
	v_mul_u32_u24_e32 v12, 0xb00, v12
	s_waitcnt lgkmcnt(4)
	v_cvt_pk_bf16_f32 v8, v16, v18
	s_waitcnt lgkmcnt(2)
	v_cvt_pk_bf16_f32 v7, v30, v32
	s_waitcnt lgkmcnt(0)
	v_cvt_pk_bf16_f32 v6, v36, v34
	v_lshl_add_u64 v[38:39], v[10:11], 0, v[164:165]
	v_lshlrev_b32_e32 v164, 1, v12
	global_store_dwordx4 v[38:39], v[6:9], off
	v_or_b32_e32 v38, v42, v25
	s_nop 0
	v_cvt_pk_bf16_f32 v9, v13, v15
	v_cvt_pk_bf16_f32 v8, v17, v19
	v_cvt_pk_bf16_f32 v7, v31, v33
	v_cvt_pk_bf16_f32 v6, v37, v35
	v_lshl_add_u64 v[12:13], v[10:11], 0, v[164:165]
	global_store_dwordx4 v[12:13], v[6:9], off
	ds_read2_b32 v[12:13], v23 offset0:214 offset1:222
	ds_read2_b32 v[14:15], v23 offset0:247 offset1:255
	ds_read2_b32 v[16:17], v23 offset0:148 offset1:156
	ds_read2_b32 v[18:19], v23 offset0:181 offset1:189
	ds_read2_b32 v[30:31], v23 offset0:82 offset1:90
	ds_read2_b32 v[32:33], v23 offset0:115 offset1:123
	ds_read2_b32 v[34:35], v23 offset0:16 offset1:24
	ds_read2_b32 v[36:37], v23 offset0:49 offset1:57
	s_waitcnt lgkmcnt(6)
	v_cvt_pk_bf16_f32 v9, v12, v14
	v_mul_u32_u24_e32 v12, 0xb00, v38
	v_lshlrev_b32_e32 v164, 1, v12
	v_or_b32_e32 v12, v42, v26
	v_mul_u32_u24_e32 v12, 0xb00, v12
	s_waitcnt lgkmcnt(4)
	v_cvt_pk_bf16_f32 v8, v16, v18
	s_waitcnt lgkmcnt(2)
	v_cvt_pk_bf16_f32 v7, v30, v32
	s_waitcnt lgkmcnt(0)
	v_cvt_pk_bf16_f32 v6, v34, v36
	v_lshl_add_u64 v[38:39], v[10:11], 0, v[164:165]
	v_lshlrev_b32_e32 v164, 1, v12
	global_store_dwordx4 v[38:39], v[6:9], off
	v_lshl_add_u64 v[10:11], v[10:11], 0, v[164:165]
	s_nop 0
	v_cvt_pk_bf16_f32 v9, v13, v15
	v_cvt_pk_bf16_f32 v8, v17, v19
	v_cvt_pk_bf16_f32 v7, v31, v33
	v_cvt_pk_bf16_f32 v6, v35, v37
	global_store_dwordx4 v[10:11], v[6:9], off
	s_waitcnt lgkmcnt(0)
.LBB0_799:
	s_andn2_saveexec_b64 s[22:23], s[22:23]
	s_cbranch_execz .LBB0_796
	s_mov_b32 s4, 0x2e8ba2e9
	v_mul_hi_i32 v6, v29, s4
	v_lshrrev_b32_e32 v8, 31, v6
	v_ashrrev_i32_e32 v6, 5, v6
	v_add_u32_e32 v30, v6, v8
	s_movk_i32 s4, 0xea00
	v_mul_lo_u32 v16, v30, s4
	v_add3_u32 v8, v5, v27, v16
	v_lshlrev_b32_e32 v6, 6, v30
	v_ashrrev_i32_e32 v9, 31, v8
	v_cmp_gt_i32_e32 vcc, s69, v8
	v_or_b32_e32 v17, v6, v20
	v_lshl_add_u64 v[8:9], v[8:9], 2, s[12:13]
	v_mov_b32_e32 v19, 0
	v_mov_b32_e32 v18, 0
	s_and_saveexec_b64 s[4:5], vcc
	s_cbranch_execz .LBB0_802
	v_mad_i64_i32 v[32:33], s[24:25], v17, s60, v[8:9]
	global_load_dword v18, v[32:33], off nt
.LBB0_802:
	s_or_b64 exec, exec, s[4:5]
	s_and_saveexec_b64 s[4:5], vcc
	s_cbranch_execz .LBB0_804
	v_or_b32_e32 v19, 2, v17
	v_mad_i64_i32 v[32:33], s[24:25], v19, s60, v[8:9]
	global_load_dword v19, v[32:33], off nt
.LBB0_804:
	s_or_b64 exec, exec, s[4:5]
	v_mov_b32_e32 v31, 0
	v_mov_b32_e32 v32, 0
	s_and_saveexec_b64 s[4:5], vcc
	s_cbranch_execz .LBB0_806
	v_or_b32_e32 v32, 4, v17
	v_mad_i64_i32 v[32:33], s[24:25], v32, s60, v[8:9]
	global_load_dword v32, v[32:33], off nt
.LBB0_806:
	s_or_b64 exec, exec, s[4:5]
	s_and_saveexec_b64 s[4:5], vcc
	s_cbranch_execz .LBB0_808
	v_or_b32_e32 v31, 6, v17
	v_mad_i64_i32 v[34:35], s[24:25], v31, s60, v[8:9]
	global_load_dword v31, v[34:35], off nt
.LBB0_808:
	s_or_b64 exec, exec, s[4:5]
	v_mov_b32_e32 v33, 0
	v_mov_b32_e32 v34, 0
	s_and_saveexec_b64 s[4:5], vcc
	s_cbranch_execz .LBB0_810
	v_or_b32_e32 v34, 8, v17
	v_mad_i64_i32 v[34:35], s[24:25], v34, s60, v[8:9]
	global_load_dword v34, v[34:35], off nt
.LBB0_810:
	s_or_b64 exec, exec, s[4:5]
	s_and_saveexec_b64 s[4:5], vcc
	s_cbranch_execz .LBB0_812
	v_or_b32_e32 v33, 10, v17
	v_mad_i64_i32 v[36:37], s[24:25], v33, s60, v[8:9]
	global_load_dword v33, v[36:37], off nt
.LBB0_812:
	s_or_b64 exec, exec, s[4:5]
	v_mov_b32_e32 v35, 0
	v_mov_b32_e32 v36, 0
	s_and_saveexec_b64 s[4:5], vcc
	s_cbranch_execz .LBB0_814
	v_or_b32_e32 v36, 12, v17
	v_mad_i64_i32 v[36:37], s[24:25], v36, s60, v[8:9]
	global_load_dword v36, v[36:37], off nt
.LBB0_814:
	s_or_b64 exec, exec, s[4:5]
	s_and_saveexec_b64 s[4:5], vcc
	s_cbranch_execz .LBB0_816
	v_or_b32_e32 v35, 14, v17
	v_mad_i64_i32 v[38:39], s[24:25], v35, s60, v[8:9]
	global_load_dword v35, v[38:39], off nt
.LBB0_816:
	s_or_b64 exec, exec, s[4:5]
	v_mov_b32_e32 v37, 0
	v_mov_b32_e32 v38, 0
	s_and_saveexec_b64 s[4:5], vcc
	s_cbranch_execz .LBB0_818
	v_or_b32_e32 v38, 16, v17
	v_mad_i64_i32 v[38:39], s[24:25], v38, s60, v[8:9]
	global_load_dword v38, v[38:39], off nt
.LBB0_818:
	s_or_b64 exec, exec, s[4:5]
	s_and_saveexec_b64 s[4:5], vcc
	s_cbranch_execz .LBB0_820
	v_or_b32_e32 v37, 18, v17
	v_mad_i64_i32 v[40:41], s[24:25], v37, s60, v[8:9]
	global_load_dword v37, v[40:41], off nt
; DI void conv_item(const float* W, int K, int N, bf16_t* WT, int mode, float* scr, int item, int lane) {
;     ...
; #pragma unroll
;     for (int i = 0; i < 32; ++i) { const int kk = 2 * i + (lane >> 5); wv[i] = okn ? W[(size_t)(k0 + kk) * N + nn] : 0.f; }
.LBB0_820:
	s_or_b64 exec, exec, s[4:5]
	v_mov_b32_e32 v39, 0
	v_mov_b32_e32 v40, 0
	s_and_saveexec_b64 s[4:5], vcc
	s_cbranch_execz .LBB0_822
	v_or_b32_e32 v40, 20, v17
	v_mad_i64_i32 v[40:41], s[24:25], v40, s60, v[8:9]
	global_load_dword v40, v[40:41], off nt
.LBB0_822:
	s_or_b64 exec, exec, s[4:5]
	s_and_saveexec_b64 s[4:5], vcc
	s_cbranch_execz .LBB0_824
	v_or_b32_e32 v39, 22, v17
	v_mad_i64_i32 v[42:43], s[24:25], v39, s60, v[8:9]
	global_load_dword v39, v[42:43], off nt
.LBB0_824:
	s_or_b64 exec, exec, s[4:5]
	v_mov_b32_e32 v41, 0
	v_mov_b32_e32 v42, 0
	s_and_saveexec_b64 s[4:5], vcc
	s_cbranch_execz .LBB0_826
	v_or_b32_e32 v42, 24, v17
	v_mad_i64_i32 v[42:43], s[24:25], v42, s60, v[8:9]
	global_load_dword v42, v[42:43], off nt
.LBB0_826:
	s_or_b64 exec, exec, s[4:5]
	s_and_saveexec_b64 s[4:5], vcc
	s_cbranch_execz .LBB0_828
	v_or_b32_e32 v41, 26, v17
	v_mad_i64_i32 v[44:45], s[24:25], v41, s60, v[8:9]
	global_load_dword v41, v[44:45], off nt
.LBB0_828:
	s_or_b64 exec, exec, s[4:5]
	v_mov_b32_e32 v43, 0
	v_mov_b32_e32 v44, 0
	s_and_saveexec_b64 s[4:5], vcc
	s_cbranch_execz .LBB0_830
	v_or_b32_e32 v44, 28, v17
	v_mad_i64_i32 v[44:45], s[24:25], v44, s60, v[8:9]
	global_load_dword v44, v[44:45], off nt
.LBB0_830:
	s_or_b64 exec, exec, s[4:5]
	s_and_saveexec_b64 s[4:5], vcc
	s_cbranch_execz .LBB0_832
	v_or_b32_e32 v43, 30, v17
	v_mad_i64_i32 v[46:47], s[24:25], v43, s60, v[8:9]
	global_load_dword v43, v[46:47], off nt
.LBB0_832:
	s_or_b64 exec, exec, s[4:5]
	v_mov_b32_e32 v45, 0
	v_mov_b32_e32 v46, 0
	s_and_saveexec_b64 s[4:5], vcc
	s_cbranch_execz .LBB0_834
	v_or_b32_e32 v46, 32, v17
	v_mad_i64_i32 v[46:47], s[24:25], v46, s60, v[8:9]
	global_load_dword v46, v[46:47], off nt
.LBB0_834:
	s_or_b64 exec, exec, s[4:5]
	s_and_saveexec_b64 s[4:5], vcc
	s_cbranch_execz .LBB0_836
	v_or_b32_e32 v45, 34, v17
	v_mad_i64_i32 v[48:49], s[24:25], v45, s60, v[8:9]
	global_load_dword v45, v[48:49], off nt
.LBB0_836:
	s_or_b64 exec, exec, s[4:5]
	v_mov_b32_e32 v47, 0
	v_mov_b32_e32 v48, 0
	s_and_saveexec_b64 s[4:5], vcc
	s_cbranch_execz .LBB0_838
	v_or_b32_e32 v48, 36, v17
	v_mad_i64_i32 v[48:49], s[24:25], v48, s60, v[8:9]
	global_load_dword v48, v[48:49], off nt
.LBB0_838:
	s_or_b64 exec, exec, s[4:5]
	s_and_saveexec_b64 s[4:5], vcc
	s_cbranch_execz .LBB0_840
	v_or_b32_e32 v47, 38, v17
	v_mad_i64_i32 v[50:51], s[24:25], v47, s60, v[8:9]
	global_load_dword v47, v[50:51], off nt
.LBB0_840:
	s_or_b64 exec, exec, s[4:5]
	v_mov_b32_e32 v49, 0
	v_mov_b32_e32 v50, 0
	s_and_saveexec_b64 s[4:5], vcc
	s_cbranch_execz .LBB0_842
	v_or_b32_e32 v50, 40, v17
	v_mad_i64_i32 v[50:51], s[24:25], v50, s60, v[8:9]
	global_load_dword v50, v[50:51], off nt
.LBB0_842:
	s_or_b64 exec, exec, s[4:5]
	s_and_saveexec_b64 s[4:5], vcc
	s_cbranch_execz .LBB0_844
	v_or_b32_e32 v49, 42, v17
	v_mad_i64_i32 v[52:53], s[24:25], v49, s60, v[8:9]
	global_load_dword v49, v[52:53], off nt
.LBB0_844:
	s_or_b64 exec, exec, s[4:5]
	v_mov_b32_e32 v51, 0
	v_mov_b32_e32 v52, 0
	s_and_saveexec_b64 s[4:5], vcc
	s_cbranch_execz .LBB0_846
	v_or_b32_e32 v52, 44, v17
	v_mad_i64_i32 v[52:53], s[24:25], v52, s60, v[8:9]
	global_load_dword v52, v[52:53], off nt
.LBB0_846:
	s_or_b64 exec, exec, s[4:5]
	s_and_saveexec_b64 s[4:5], vcc
	s_cbranch_execz .LBB0_848
	v_or_b32_e32 v51, 46, v17
	v_mad_i64_i32 v[54:55], s[24:25], v51, s60, v[8:9]
	global_load_dword v51, v[54:55], off nt
.LBB0_848:
	s_or_b64 exec, exec, s[4:5]
	v_mov_b32_e32 v53, 0
	v_mov_b32_e32 v54, 0
	s_and_saveexec_b64 s[4:5], vcc
	s_cbranch_execz .LBB0_850
	v_or_b32_e32 v54, 48, v17
	v_mad_i64_i32 v[54:55], s[24:25], v54, s60, v[8:9]
	global_load_dword v54, v[54:55], off nt
.LBB0_850:
	s_or_b64 exec, exec, s[4:5]
	s_and_saveexec_b64 s[4:5], vcc
	s_cbranch_execz .LBB0_852
	v_or_b32_e32 v53, 50, v17
	v_mad_i64_i32 v[56:57], s[24:25], v53, s60, v[8:9]
	global_load_dword v53, v[56:57], off nt
.LBB0_852:
	s_or_b64 exec, exec, s[4:5]
	v_mov_b32_e32 v55, 0
	v_mov_b32_e32 v56, 0
	s_and_saveexec_b64 s[4:5], vcc
	s_cbranch_execz .LBB0_854
	v_or_b32_e32 v56, 52, v17
	v_mad_i64_i32 v[56:57], s[24:25], v56, s60, v[8:9]
	global_load_dword v56, v[56:57], off nt
.LBB0_854:
	s_or_b64 exec, exec, s[4:5]
	s_and_saveexec_b64 s[4:5], vcc
	s_cbranch_execz .LBB0_856
	v_or_b32_e32 v55, 54, v17
	v_mad_i64_i32 v[58:59], s[24:25], v55, s60, v[8:9]
	global_load_dword v55, v[58:59], off nt
.LBB0_856:
	s_or_b64 exec, exec, s[4:5]
	v_mov_b32_e32 v57, 0
	v_mov_b32_e32 v58, 0
	s_and_saveexec_b64 s[4:5], vcc
	s_cbranch_execz .LBB0_858
	v_or_b32_e32 v58, 56, v17
	v_mad_i64_i32 v[58:59], s[24:25], v58, s60, v[8:9]
	global_load_dword v58, v[58:59], off nt
.LBB0_858:
	s_or_b64 exec, exec, s[4:5]
	s_and_saveexec_b64 s[4:5], vcc
	s_cbranch_execz .LBB0_860
	v_or_b32_e32 v57, 58, v17
	v_mad_i64_i32 v[60:61], s[24:25], v57, s60, v[8:9]
	global_load_dword v57, v[60:61], off nt
.LBB0_860:
	s_or_b64 exec, exec, s[4:5]
	v_mov_b32_e32 v59, 0
	v_mov_b32_e32 v60, 0
	s_and_saveexec_b64 s[4:5], vcc
	s_cbranch_execz .LBB0_862
	v_or_b32_e32 v60, 60, v17
	v_mad_i64_i32 v[60:61], s[24:25], v60, s60, v[8:9]
	global_load_dword v60, v[60:61], off nt
.LBB0_862:
	s_or_b64 exec, exec, s[4:5]
	s_and_saveexec_b64 s[4:5], vcc
	s_cbranch_execz .LBB0_864
	v_or_b32_e32 v17, 62, v17
	v_mad_i64_i32 v[8:9], s[24:25], v17, s60, v[8:9]
	global_load_dword v59, v[8:9], off nt

; DI void conv_item(const float* W, int K, int N, bf16_t* WT, int mode, float* scr, int item, int lane) {
;     ...
; #pragma unroll
;     for (int i = 0; i < 32; ++i) { const int kk = 2 * i + (lane >> 5); wv[i] = okn ? W[(size_t)(k0 + kk) * N + nn] : 0.f; }
; #pragma unroll
;     for (int i = 0; i < 32; ++i) { const int kk = 2 * i + (lane >> 5); scr[kk * 33 + (lane & 31)] = wv[i]; }
; DI void convert_mix(const Params& p, int l, unsigned char* lds, int tid, int gw, int NGW) {
;     ...
;     for (int it = gw; it < IIN + 3 * IB + IO; it += NGW) { int r = it;
;         if (r < IIN) { conv_item(win, DM, 7440, (bf16_t*)(p.ws + OFF_WINT), 2, scr, r, lane); continue; } r -= IIN;
;         if (r < 3 * IB) { const int g = r / IB; conv_item(wb + (size_t)g * 512 * DM, 512, DM, (bf16_t*)(p.ws + OFF_WBT) + (size_t)g * DM * 512, 0, scr, r % IB, lane); continue; } r -= 3 * IB;
;         conv_item(wo, DM, DM, (bf16_t*)(p.ws + OFF_WOT), 0, scr, r, lane); }
.LBB0_895:
	s_movk_i32 s4, 0xe8f
	v_cmp_lt_i32_e32 vcc, s4, v30
	s_and_saveexec_b64 s[4:5], vcc
	s_xor_b64 s[26:27], exec, s[4:5]
	s_cbranch_execz .LBB0_901
	s_movk_i32 s4, 0x118f
	v_cmp_lt_u32_e32 vcc, s4, v30
	s_and_saveexec_b64 s[4:5], vcc
	s_xor_b64 s[28:29], exec, s[4:5]
	s_cbranch_execz .LBB0_898
	v_add_u32_e32 v8, 0xfffdce00, v28
	v_and_b32_e32 v31, 0x3e0, v8
	v_and_b32_e32 v7, 0x1ffc0, v29
	v_or_b32_e32 v8, v31, v1
	v_or_b32_e32 v10, v7, v21
	v_lshlrev_b32_e32 v164, 2, v8
	v_lshl_add_u64 v[8:9], s[16:17], 0, v[164:165]
	v_lshlrev_b32_e32 v164, 12, v10
	v_lshl_add_u64 v[8:9], v[8:9], 0, v[164:165]
	v_add_co_u32_e32 v10, vcc, 0x2000, v8
	s_mov_b32 s4, 0x10000
	s_nop 0
	v_addc_co_u32_e32 v11, vcc, 0, v9, vcc
	v_add_co_u32_e32 v12, vcc, 0x4000, v8
	v_lshlrev_b32_e32 v164, 1, v7
	s_nop 0
	v_addc_co_u32_e32 v13, vcc, 0, v9, vcc
	v_add_co_u32_e32 v14, vcc, 0x6000, v8
	v_or_b32_e32 v7, v31, v23
	s_nop 0
	v_addc_co_u32_e32 v15, vcc, 0, v9, vcc
	v_add_co_u32_e32 v16, vcc, 0x8000, v8
	s_nop 1
	v_addc_co_u32_e32 v17, vcc, 0, v9, vcc
	v_add_co_u32_e32 v18, vcc, 0xa000, v8
	s_nop 1
	v_addc_co_u32_e32 v19, vcc, 0, v9, vcc
	v_add_co_u32_e32 v32, vcc, 0xc000, v8
	s_nop 1
	v_addc_co_u32_e32 v33, vcc, 0, v9, vcc
	v_add_co_u32_e32 v34, vcc, 0xe000, v8
	s_nop 1
	v_addc_co_u32_e32 v35, vcc, 0, v9, vcc
	global_load_dword v38, v[8:9], off nt
	global_load_dword v39, v[10:11], off nt
	global_load_dword v40, v[12:13], off nt
	global_load_dword v41, v[14:15], off nt
	global_load_dword v42, v[16:17], off nt
	global_load_dword v43, v[18:19], off nt
	global_load_dword v44, v[32:33], off nt
	global_load_dword v45, v[34:35], off nt
	v_add_co_u32_e32 v10, vcc, s4, v8
	s_mov_b32 s4, 0x14000
	s_nop 0
	v_addc_co_u32_e32 v11, vcc, 0, v9, vcc
	v_add_co_u32_e32 v12, vcc, 0x12000, v8
	s_nop 1
	v_addc_co_u32_e32 v13, vcc, 0, v9, vcc
	v_add_co_u32_e32 v14, vcc, s4, v8
	s_mov_b32 s4, 0x18000
	s_nop 0
	v_addc_co_u32_e32 v15, vcc, 0, v9, vcc
	v_add_co_u32_e32 v16, vcc, 0x16000, v8
	s_nop 1
	v_addc_co_u32_e32 v17, vcc, 0, v9, vcc
	v_add_co_u32_e32 v18, vcc, s4, v8
	s_mov_b32 s4, 0x1c000
	s_nop 0
	v_addc_co_u32_e32 v19, vcc, 0, v9, vcc
	v_add_co_u32_e32 v32, vcc, 0x1a000, v8
	s_nop 1
	v_addc_co_u32_e32 v33, vcc, 0, v9, vcc
	v_add_co_u32_e32 v34, vcc, s4, v8
	s_mov_b32 s4, 0x30000
	s_nop 0
	v_addc_co_u32_e32 v35, vcc, 0, v9, vcc
	v_add_co_u32_e32 v36, vcc, 0x1e000, v8
	s_nop 1
	v_addc_co_u32_e32 v37, vcc, 0, v9, vcc
	global_load_dword v46, v[10:11], off nt
	global_load_dword v47, v[12:13], off nt
	global_load_dword v48, v[14:15], off nt
	global_load_dword v49, v[16:17], off nt
	global_load_dword v50, v[18:19], off nt
	global_load_dword v51, v[32:33], off nt
	global_load_dword v52, v[34:35], off nt
	global_load_dword v53, v[36:37], off nt
	v_add_co_u32_e32 v10, vcc, 0x20000, v8
	s_nop 1
	v_addc_co_u32_e32 v11, vcc, 0, v9, vcc
	v_add_co_u32_e32 v12, vcc, 0x22000, v8
	s_nop 1
	v_addc_co_u32_e32 v13, vcc, 0, v9, vcc
	v_add_co_u32_e32 v14, vcc, 0x24000, v8
	s_nop 1
	v_addc_co_u32_e32 v15, vcc, 0, v9, vcc
	v_add_co_u32_e32 v16, vcc, 0x26000, v8
	s_nop 1
	v_addc_co_u32_e32 v17, vcc, 0, v9, vcc
	v_add_co_u32_e32 v18, vcc, 0x28000, v8
	s_nop 1
	v_addc_co_u32_e32 v19, vcc, 0, v9, vcc
	v_add_co_u32_e32 v32, vcc, 0x2a000, v8
	s_nop 1
	v_addc_co_u32_e32 v33, vcc, 0, v9, vcc
	v_add_co_u32_e32 v34, vcc, 0x2c000, v8
	s_nop 1
	v_addc_co_u32_e32 v35, vcc, 0, v9, vcc
	v_add_co_u32_e32 v36, vcc, 0x2e000, v8
	s_nop 1
	v_addc_co_u32_e32 v37, vcc, 0, v9, vcc
	global_load_dword v54, v[10:11], off nt
	global_load_dword v55, v[12:13], off nt
	global_load_dword v56, v[14:15], off nt
	global_load_dword v57, v[16:17], off nt
	global_load_dword v58, v[18:19], off nt
	global_load_dword v59, v[32:33], off nt
	global_load_dword v60, v[34:35], off nt
	s_nop 0
	global_load_dword v36, v[36:37], off nt
	v_add_co_u32_e32 v10, vcc, s4, v8
	s_nop 1
	v_addc_co_u32_e32 v11, vcc, 0, v9, vcc
	v_add_co_u32_e32 v12, vcc, 0x32000, v8
	s_nop 1
	v_addc_co_u32_e32 v13, vcc, 0, v9, vcc
	v_add_co_u32_e32 v14, vcc, 0x34000, v8
	s_nop 1
	v_addc_co_u32_e32 v15, vcc, 0, v9, vcc
	v_add_co_u32_e32 v16, vcc, 0x36000, v8
	s_nop 1
	v_addc_co_u32_e32 v17, vcc, 0, v9, vcc
	v_add_co_u32_e32 v18, vcc, 0x38000, v8
	s_nop 1
	v_addc_co_u32_e32 v19, vcc, 0, v9, vcc
	v_add_co_u32_e32 v32, vcc, 0x3a000, v8
	s_nop 1
	v_addc_co_u32_e32 v33, vcc, 0, v9, vcc
	v_add_co_u32_e32 v34, vcc, 0x3c000, v8
	s_nop 1
	v_addc_co_u32_e32 v35, vcc, 0, v9, vcc
	v_add_co_u32_e32 v8, vcc, 0x3e000, v8
	s_nop 1
	v_addc_co_u32_e32 v9, vcc, 0, v9, vcc
	global_load_dword v10, v[10:11], off nt
	s_nop 0
	global_load_dword v11, v[12:13], off nt
	s_nop 0
	global_load_dword v12, v[14:15], off nt
	global_load_dword v13, v[16:17], off nt
	s_nop 0
	global_load_dword v14, v[18:19], off nt
	global_load_dword v15, v[32:33], off nt
	global_load_dword v16, v[34:35], off nt
	s_nop 0
	global_load_dword v8, v[8:9], off nt
	v_add_u32_e32 v9, 0x400, v22
	s_waitcnt vmcnt(30)
	ds_write2_b32 v22, v38, v39 offset1:66
	s_waitcnt vmcnt(28)
	ds_write2_b32 v22, v40, v41 offset0:132 offset1:198
	s_waitcnt vmcnt(26)
	ds_write2_b32 v9, v42, v43 offset0:8 offset1:74
	s_waitcnt vmcnt(24)
	ds_write2_b32 v9, v44, v45 offset0:140 offset1:206
	v_add_u32_e32 v9, 0x800, v22
	s_waitcnt vmcnt(22)
	ds_write2_b32 v9, v46, v47 offset0:16 offset1:82
	s_waitcnt vmcnt(20)
	ds_write2_b32 v9, v48, v49 offset0:148 offset1:214
	v_add_u32_e32 v9, 0xc00, v22
	s_waitcnt vmcnt(18)
	ds_write2_b32 v9, v50, v51 offset0:24 offset1:90
	s_waitcnt vmcnt(16)
	ds_write2_b32 v9, v52, v53 offset0:156 offset1:222
	v_add_u32_e32 v9, 0x1000, v22
	s_waitcnt vmcnt(14)
	ds_write2_b32 v9, v54, v55 offset0:32 offset1:98
	s_waitcnt vmcnt(12)
; DI unsigned pk2(float lo, float hi) { f32x2_t v = {lo, hi}; bf16x2_t b = __builtin_convertvector(v, bf16x2_t); return __builtin_bit_cast(unsigned, b); }
; DI void conv_item(const float* W, int K, int N, bf16_t* WT, int mode, float* scr, int item, int lane) {
;     ...
;     for (int i = 0; i < 32; ++i) { const int kk = 2 * i + (lane >> 5); scr[kk * 33 + (lane & 31)] = wv[i]; }
;     asm volatile("s_waitcnt lgkmcnt(0)" ::: "memory");
;     const int c = lane & 7;
; #pragma unroll
;     for (int j = 0; j < 4; ++j) { const int n = (lane >> 3) + 8 * j; const float* s = scr + (8 * c) * 33 + n;
;         u32x4 o; o.x = pk2(s[0 * 33], s[1 * 33]); o.y = pk2(s[2 * 33], s[3 * 33]); o.z = pk2(s[4 * 33], s[5 * 33]); o.w = pk2(s[6 * 33], s[7 * 33]);
;         if (n0 + n < N) *(u32x4*)(WT + (size_t)dstrow(mode, n0 + n) * K + k0 + 8 * c) = o; }
;     asm volatile("s_waitcnt lgkmcnt(0)" ::: "memory");
; }
; DI void convert_mix(const Params& p, int l, unsigned char* lds, int tid, int gw, int NGW) {
;     ...
;         if (r < 3 * IB) { const int g = r / IB; conv_item(wb + (size_t)g * 512 * DM, 512, DM, (bf16_t*)(p.ws + OFF_WBT) + (size_t)g * DM * 512, 0, scr, r % IB, lane); continue; } r -= 3 * IB;
	ds_write2_b32 v9, v56, v57 offset0:164 offset1:230
	v_add_u32_e32 v9, 0x1400, v22
	s_waitcnt vmcnt(10)
	ds_write2_b32 v9, v58, v59 offset0:40 offset1:106
	s_waitcnt vmcnt(8)
	ds_write2_b32 v9, v60, v36 offset0:172 offset1:238
	v_add_u32_e32 v9, 0x1800, v22
	s_waitcnt vmcnt(6)
	ds_write2_b32 v9, v10, v11 offset0:48 offset1:114
	s_waitcnt vmcnt(4)
	ds_write2_b32 v9, v12, v13 offset0:180 offset1:246
	v_add_u32_e32 v9, 0x1c00, v22
	s_waitcnt vmcnt(2)
	ds_write2_b32 v9, v14, v15 offset0:56 offset1:122
	s_waitcnt vmcnt(0)
	ds_write2_b32 v9, v16, v8 offset0:188 offset1:254
	s_waitcnt lgkmcnt(0)
	ds_read2_b32 v[14:15], v24 offset0:198 offset1:206
	ds_read2_b32 v[16:17], v24 offset0:231 offset1:239
	ds_read2_b32 v[18:19], v24 offset0:132 offset1:140
	ds_read2_b32 v[32:33], v24 offset0:165 offset1:173
	ds_read2_b32 v[34:35], v24 offset0:66 offset1:74
	ds_read2_b32 v[36:37], v24 offset0:99 offset1:107
	ds_read2_b32 v[38:39], v24 offset0:33 offset1:41
	ds_read2_b32 v[40:41], v24 offset1:8
	v_lshl_add_u64 v[12:13], v[2:3], 0, v[164:165]
	v_lshlrev_b32_e32 v164, 11, v7
	v_or_b32_e32 v7, v31, v25
	s_waitcnt lgkmcnt(6)
	v_cvt_pk_bf16_f32 v11, v14, v16
	s_waitcnt lgkmcnt(4)
	v_cvt_pk_bf16_f32 v10, v18, v32
	s_waitcnt lgkmcnt(2)
	v_cvt_pk_bf16_f32 v9, v34, v36
	s_waitcnt lgkmcnt(0)
	v_cvt_pk_bf16_f32 v8, v40, v38
	v_lshl_add_u64 v[42:43], v[12:13], 0, v[164:165]
	v_lshlrev_b32_e32 v164, 11, v7
	global_store_dwordx4 v[42:43], v[8:11], off
	v_or_b32_e32 v7, v31, v26
	s_nop 0
	v_cvt_pk_bf16_f32 v11, v15, v17
	v_cvt_pk_bf16_f32 v10, v19, v33
	v_cvt_pk_bf16_f32 v9, v35, v37
	v_cvt_pk_bf16_f32 v8, v41, v39
	v_lshl_add_u64 v[14:15], v[12:13], 0, v[164:165]
	global_store_dwordx4 v[14:15], v[8:11], off
	ds_read2_b32 v[14:15], v24 offset0:214 offset1:222
	ds_read2_b32 v[16:17], v24 offset0:247 offset1:255
	ds_read2_b32 v[18:19], v24 offset0:148 offset1:156
	ds_read2_b32 v[32:33], v24 offset0:181 offset1:189
	ds_read2_b32 v[34:35], v24 offset0:82 offset1:90
	ds_read2_b32 v[36:37], v24 offset0:115 offset1:123
	ds_read2_b32 v[38:39], v24 offset0:49 offset1:57
	ds_read2_b32 v[40:41], v24 offset0:16 offset1:24
	v_lshlrev_b32_e32 v164, 11, v7
	v_or_b32_e32 v7, v31, v27
	s_waitcnt lgkmcnt(6)
	v_cvt_pk_bf16_f32 v11, v14, v16
	s_waitcnt lgkmcnt(4)
	v_cvt_pk_bf16_f32 v10, v18, v32
	s_waitcnt lgkmcnt(2)
	v_cvt_pk_bf16_f32 v9, v34, v36
	s_waitcnt lgkmcnt(0)
	v_cvt_pk_bf16_f32 v8, v40, v38
	v_lshl_add_u64 v[42:43], v[12:13], 0, v[164:165]
	v_lshlrev_b32_e32 v164, 11, v7
	global_store_dwordx4 v[42:43], v[8:11], off
	v_lshl_add_u64 v[12:13], v[12:13], 0, v[164:165]
	s_nop 0
	v_cvt_pk_bf16_f32 v11, v15, v17
	v_cvt_pk_bf16_f32 v10, v19, v33
	v_cvt_pk_bf16_f32 v9, v35, v37
	v_cvt_pk_bf16_f32 v8, v41, v39
	global_store_dwordx4 v[12:13], v[8:11], off
	s_waitcnt lgkmcnt(0)
.LBB0_898:
	s_andn2_saveexec_b64 s[28:29], s[28:29]
	s_cbranch_execz .LBB0_900
	v_add_u32_e32 v7, 0xfffff170, v30
	v_add_u32_e32 v12, 0xfffe2e00, v28
	v_lshrrev_b32_e32 v164, 8, v7
	v_add_u32_e32 v7, 0x600, v29
	v_and_b32_e32 v31, 0x3e0, v12
	v_lshlrev_b64 v[8:9], 21, v[164:165]
	v_and_b32_e32 v7, 0x1c0, v7
	v_or_b32_e32 v12, v31, v1
	v_lshl_add_u64 v[8:9], s[14:15], 0, v[8:9]
	v_lshlrev_b64 v[10:11], 20, v[164:165]
	v_or_b32_e32 v13, v7, v21
	v_lshlrev_b32_e32 v164, 2, v12
	v_lshl_add_u64 v[8:9], v[8:9], 0, v[164:165]
	v_lshlrev_b32_e32 v164, 12, v13
	v_lshl_add_u64 v[8:9], v[8:9], 0, v[164:165]
	s_movk_i32 s4, 0x2000
	v_add_co_u32_e32 v12, vcc, s4, v8
	s_movk_i32 s4, 0x6000
	s_nop 0
	v_addc_co_u32_e32 v13, vcc, 0, v9, vcc
	v_add_co_u32_e32 v14, vcc, s85, v8
	v_lshlrev_b32_e32 v164, 1, v7
	s_nop 0
	v_addc_co_u32_e32 v15, vcc, 0, v9, vcc
	v_add_co_u32_e32 v16, vcc, s4, v8
	s_mov_b32 s4, 0x8000
	s_nop 0
	v_addc_co_u32_e32 v17, vcc, 0, v9, vcc
	v_add_co_u32_e32 v18, vcc, s4, v8
	s_mov_b32 s4, 0xa000
	s_nop 0
	v_addc_co_u32_e32 v19, vcc, 0, v9, vcc
	v_add_co_u32_e32 v32, vcc, s4, v8
	s_mov_b32 s4, 0xc000
	s_nop 0
	v_addc_co_u32_e32 v33, vcc, 0, v9, vcc
	v_add_co_u32_e32 v34, vcc, s4, v8
	s_mov_b32 s4, 0xe000
	s_nop 0
	v_addc_co_u32_e32 v35, vcc, 0, v9, vcc
	v_add_co_u32_e32 v36, vcc, s4, v8
	s_mov_b32 s4, 0x10000
	s_nop 0
	v_addc_co_u32_e32 v37, vcc, 0, v9, vcc
	global_load_dword v40, v[8:9], off nt
	global_load_dword v41, v[12:13], off nt
	global_load_dword v42, v[14:15], off nt
	global_load_dword v43, v[16:17], off nt
	global_load_dword v44, v[18:19], off nt
	global_load_dword v45, v[32:33], off nt
	global_load_dword v46, v[34:35], off nt
	global_load_dword v47, v[36:37], off nt
	v_add_co_u32_e32 v12, vcc, s4, v8
	s_mov_b32 s4, 0x12000
	s_nop 0
	v_addc_co_u32_e32 v13, vcc, 0, v9, vcc
	v_add_co_u32_e32 v14, vcc, s4, v8
	s_mov_b32 s4, 0x14000
	s_nop 0
	v_addc_co_u32_e32 v15, vcc, 0, v9, vcc
	v_add_co_u32_e32 v16, vcc, s4, v8
	s_mov_b32 s4, 0x16000
	s_nop 0
	v_addc_co_u32_e32 v17, vcc, 0, v9, vcc
	v_add_co_u32_e32 v18, vcc, s4, v8
	s_mov_b32 s4, 0x18000
	s_nop 0
	v_addc_co_u32_e32 v19, vcc, 0, v9, vcc
	v_add_co_u32_e32 v32, vcc, s4, v8
	s_mov_b32 s4, 0x1a000
	s_nop 0
	v_addc_co_u32_e32 v33, vcc, 0, v9, vcc
	v_add_co_u32_e32 v34, vcc, s4, v8
	s_mov_b32 s4, 0x1c000
	s_nop 0
	v_addc_co_u32_e32 v35, vcc, 0, v9, vcc
	v_add_co_u32_e32 v36, vcc, s4, v8
	s_mov_b32 s4, 0x1e000
	s_nop 0
	v_addc_co_u32_e32 v37, vcc, 0, v9, vcc
	v_add_co_u32_e32 v38, vcc, s4, v8
	s_mov_b32 s4, 0x20000
	s_nop 0
	v_addc_co_u32_e32 v39, vcc, 0, v9, vcc
	global_load_dword v48, v[12:13], off nt
	global_load_dword v49, v[14:15], off nt
	global_load_dword v50, v[16:17], off nt
	global_load_dword v51, v[18:19], off nt
	global_load_dword v52, v[32:33], off nt
	global_load_dword v53, v[34:35], off nt
	global_load_dword v54, v[36:37], off nt
; DI unsigned pk2(float lo, float hi) { f32x2_t v = {lo, hi}; bf16x2_t b = __builtin_convertvector(v, bf16x2_t); return __builtin_bit_cast(unsigned, b); }
; DI void conv_item(const float* W, int K, int N, bf16_t* WT, int mode, float* scr, int item, int lane) {
;     ...
;     for (int i = 0; i < 32; ++i) { const int kk = 2 * i + (lane >> 5); wv[i] = okn ? W[(size_t)(k0 + kk) * N + nn] : 0.f; }
; #pragma unroll
;     for (int i = 0; i < 32; ++i) { const int kk = 2 * i + (lane >> 5); scr[kk * 33 + (lane & 31)] = wv[i]; }
;     asm volatile("s_waitcnt lgkmcnt(0)" ::: "memory");
;     const int c = lane & 7;
; #pragma unroll
;     for (int j = 0; j < 4; ++j) { const int n = (lane >> 3) + 8 * j; const float* s = scr + (8 * c) * 33 + n;
;         u32x4 o; o.x = pk2(s[0 * 33], s[1 * 33]); o.y = pk2(s[2 * 33], s[3 * 33]); o.z = pk2(s[4 * 33], s[5 * 33]); o.w = pk2(s[6 * 33], s[7 * 33]);
;         if (n0 + n < N) *(u32x4*)(WT + (size_t)dstrow(mode, n0 + n) * K + k0 + 8 * c) = o; }
	global_load_dword v55, v[38:39], off nt
	v_add_co_u32_e32 v12, vcc, s4, v8
	s_mov_b32 s4, 0x22000
	s_nop 0
	v_addc_co_u32_e32 v13, vcc, 0, v9, vcc
	v_add_co_u32_e32 v14, vcc, s4, v8
	s_mov_b32 s4, 0x24000
	s_nop 0
	v_addc_co_u32_e32 v15, vcc, 0, v9, vcc
	v_add_co_u32_e32 v16, vcc, s4, v8
	s_mov_b32 s4, 0x26000
	s_nop 0
	v_addc_co_u32_e32 v17, vcc, 0, v9, vcc
	v_add_co_u32_e32 v18, vcc, s4, v8
	s_mov_b32 s4, 0x28000
	s_nop 0
	v_addc_co_u32_e32 v19, vcc, 0, v9, vcc
	v_add_co_u32_e32 v32, vcc, s4, v8
	s_mov_b32 s4, 0x2a000
	s_nop 0
	v_addc_co_u32_e32 v33, vcc, 0, v9, vcc
	v_add_co_u32_e32 v34, vcc, s4, v8
	s_mov_b32 s4, 0x2c000
	s_nop 0
	v_addc_co_u32_e32 v35, vcc, 0, v9, vcc
	v_add_co_u32_e32 v36, vcc, s4, v8
	s_mov_b32 s4, 0x2e000
	s_nop 0
	v_addc_co_u32_e32 v37, vcc, 0, v9, vcc
	v_add_co_u32_e32 v38, vcc, s4, v8
	s_mov_b32 s4, 0x30000
	s_nop 0
	v_addc_co_u32_e32 v39, vcc, 0, v9, vcc
	global_load_dword v56, v[12:13], off nt
	global_load_dword v57, v[14:15], off nt
	global_load_dword v58, v[16:17], off nt
	global_load_dword v59, v[18:19], off nt
	global_load_dword v60, v[32:33], off nt
	global_load_dword v61, v[34:35], off nt
	global_load_dword v62, v[36:37], off nt
	s_nop 0
	global_load_dword v38, v[38:39], off nt
	v_add_co_u32_e32 v12, vcc, s4, v8
	s_mov_b32 s4, 0x32000
	s_nop 0
	v_addc_co_u32_e32 v13, vcc, 0, v9, vcc
	v_add_co_u32_e32 v14, vcc, s4, v8
	s_mov_b32 s4, 0x34000
	s_nop 0
	v_addc_co_u32_e32 v15, vcc, 0, v9, vcc
	v_add_co_u32_e32 v16, vcc, s4, v8
	s_mov_b32 s4, 0x36000
	s_nop 0
	v_addc_co_u32_e32 v17, vcc, 0, v9, vcc
	v_add_co_u32_e32 v18, vcc, s4, v8
	s_mov_b32 s4, 0x38000
	s_nop 0
	v_addc_co_u32_e32 v19, vcc, 0, v9, vcc
	v_add_co_u32_e32 v32, vcc, s4, v8
	s_mov_b32 s4, 0x3a000
	s_nop 0
	v_addc_co_u32_e32 v33, vcc, 0, v9, vcc
	v_add_co_u32_e32 v34, vcc, s4, v8
	s_mov_b32 s4, 0x3c000
	s_nop 0
	v_addc_co_u32_e32 v35, vcc, 0, v9, vcc
	v_add_co_u32_e32 v36, vcc, s4, v8
	s_mov_b32 s4, 0x3e000
	s_nop 0
	v_addc_co_u32_e32 v37, vcc, 0, v9, vcc
	v_add_co_u32_e32 v8, vcc, s4, v8
	v_mov_b32_e32 v7, v165
	s_nop 0
	v_addc_co_u32_e32 v9, vcc, 0, v9, vcc
	global_load_dword v12, v[12:13], off nt
	s_nop 0
	global_load_dword v13, v[14:15], off nt
	s_nop 0
	global_load_dword v14, v[16:17], off nt
	global_load_dword v15, v[18:19], off nt
	s_nop 0
	global_load_dword v16, v[32:33], off nt
	global_load_dword v17, v[34:35], off nt
	global_load_dword v18, v[36:37], off nt
	global_load_dword v19, v[8:9], off nt
	v_lshl_add_u64 v[8:9], s[22:23], 0, v[10:11]
	v_add_u32_e32 v10, 0x400, v22
	s_waitcnt vmcnt(30)
	ds_write2_b32 v22, v40, v41 offset1:66
	s_waitcnt vmcnt(28)
	ds_write2_b32 v22, v42, v43 offset0:132 offset1:198
	s_waitcnt vmcnt(26)
	ds_write2_b32 v10, v44, v45 offset0:8 offset1:74
	s_waitcnt vmcnt(24)
	ds_write2_b32 v10, v46, v47 offset0:140 offset1:206
	v_add_u32_e32 v10, 0x800, v22
	s_waitcnt vmcnt(22)
	ds_write2_b32 v10, v48, v49 offset0:16 offset1:82
	s_waitcnt vmcnt(20)
	ds_write2_b32 v10, v50, v51 offset0:148 offset1:214
	v_add_u32_e32 v10, 0xc00, v22
	s_waitcnt vmcnt(18)
	ds_write2_b32 v10, v52, v53 offset0:24 offset1:90
	s_waitcnt vmcnt(16)
	ds_write2_b32 v10, v54, v55 offset0:156 offset1:222
	v_add_u32_e32 v10, 0x1000, v22
	s_waitcnt vmcnt(14)
	ds_write2_b32 v10, v56, v57 offset0:32 offset1:98
	s_waitcnt vmcnt(12)
	ds_write2_b32 v10, v58, v59 offset0:164 offset1:230
	v_add_u32_e32 v10, 0x1400, v22
	s_waitcnt vmcnt(10)
	ds_write2_b32 v10, v60, v61 offset0:40 offset1:106
	s_waitcnt vmcnt(8)
	ds_write2_b32 v10, v62, v38 offset0:172 offset1:238
	v_add_u32_e32 v10, 0x1800, v22
	s_waitcnt vmcnt(6)
	ds_write2_b32 v10, v12, v13 offset0:48 offset1:114
	s_waitcnt vmcnt(4)
	ds_write2_b32 v10, v14, v15 offset0:180 offset1:246
	v_add_u32_e32 v10, 0x1c00, v22
	s_waitcnt vmcnt(2)
	ds_write2_b32 v10, v16, v17 offset0:56 offset1:122
	s_waitcnt vmcnt(0)
	ds_write2_b32 v10, v18, v19 offset0:188 offset1:254
	s_waitcnt lgkmcnt(0)
	ds_read2_b32 v[14:15], v24 offset0:198 offset1:206
	ds_read2_b32 v[16:17], v24 offset0:231 offset1:239
	ds_read2_b32 v[18:19], v24 offset0:132 offset1:140
	ds_read2_b32 v[32:33], v24 offset0:165 offset1:173
	ds_read2_b32 v[34:35], v24 offset0:66 offset1:74
	ds_read2_b32 v[36:37], v24 offset0:99 offset1:107
	ds_read2_b32 v[38:39], v24 offset0:33 offset1:41
	ds_read2_b32 v[40:41], v24 offset1:8
	v_lshl_add_u64 v[8:9], v[8:9], 0, v[164:165]
	v_lshl_add_u64 v[12:13], v[8:9], 0, v[6:7]
	v_or_b32_e32 v7, v31, v23
	v_lshlrev_b32_e32 v164, 10, v7
	v_or_b32_e32 v7, v31, v25
	s_waitcnt lgkmcnt(6)
	v_cvt_pk_bf16_f32 v11, v14, v16
	s_waitcnt lgkmcnt(4)
	v_cvt_pk_bf16_f32 v10, v18, v32
	s_waitcnt lgkmcnt(2)
	v_cvt_pk_bf16_f32 v9, v34, v36
	s_waitcnt lgkmcnt(0)
	v_cvt_pk_bf16_f32 v8, v40, v38
	v_lshl_add_u64 v[42:43], v[12:13], 0, v[164:165]
	v_lshlrev_b32_e32 v164, 10, v7
	global_store_dwordx4 v[42:43], v[8:11], off
	v_or_b32_e32 v7, v31, v26
	s_nop 0
	v_cvt_pk_bf16_f32 v11, v15, v17
	v_cvt_pk_bf16_f32 v10, v19, v33
	v_cvt_pk_bf16_f32 v9, v35, v37
	v_cvt_pk_bf16_f32 v8, v41, v39
	v_lshl_add_u64 v[14:15], v[12:13], 0, v[164:165]
	global_store_dwordx4 v[14:15], v[8:11], off
	ds_read2_b32 v[14:15], v24 offset0:214 offset1:222
	ds_read2_b32 v[16:17], v24 offset0:247 offset1:255
	ds_read2_b32 v[18:19], v24 offset0:148 offset1:156
	ds_read2_b32 v[32:33], v24 offset0:181 offset1:189
	ds_read2_b32 v[34:35], v24 offset0:82 offset1:90
	ds_read2_b32 v[36:37], v24 offset0:115 offset1:123
	ds_read2_b32 v[38:39], v24 offset0:49 offset1:57
	ds_read2_b32 v[40:41], v24 offset0:16 offset1:24
	v_lshlrev_b32_e32 v164, 10, v7
	v_or_b32_e32 v7, v31, v27
	s_waitcnt lgkmcnt(6)
	v_cvt_pk_bf16_f32 v11, v14, v16
	s_waitcnt lgkmcnt(4)
	v_cvt_pk_bf16_f32 v10, v18, v32
	s_waitcnt lgkmcnt(2)
	v_cvt_pk_bf16_f32 v9, v34, v36
	s_waitcnt lgkmcnt(0)
	v_cvt_pk_bf16_f32 v8, v40, v38
	v_lshl_add_u64 v[42:43], v[12:13], 0, v[164:165]
	v_lshlrev_b32_e32 v164, 10, v7
	global_store_dwordx4 v[42:43], v[8:11], off
	v_lshl_add_u64 v[12:13], v[12:13], 0, v[164:165]
	s_nop 0
	v_cvt_pk_bf16_f32 v11, v15, v17
	v_cvt_pk_bf16_f32 v10, v19, v33
	v_cvt_pk_bf16_f32 v9, v35, v37
	v_cvt_pk_bf16_f32 v8, v41, v39
	global_store_dwordx4 v[12:13], v[8:11], off
	s_waitcnt lgkmcnt(0)

; DI void conv_item(const float* W, int K, int N, bf16_t* WT, int mode, float* scr, int item, int lane) {
;     const int nblk = (N + 31) / 32, kb = item / nblk, nb = item % nblk, k0 = 64 * kb, n0 = 32 * nb;
;     const int nn = n0 + (lane & 31); const bool okn = nn < N;
;     float wv[32];
; #pragma unroll
;     for (int i = 0; i < 32; ++i) { const int kk = 2 * i + (lane >> 5); wv[i] = okn ? W[(size_t)(k0 + kk) * N + nn] : 0.f; }
; DI void convert_mix(const Params& p, int l, unsigned char* lds, int tid, int gw, int NGW) {
;     ...
;         if (r < IIN) { conv_item(win, DM, 7440, (bf16_t*)(p.ws + OFF_WINT), 2, scr, r, lane); continue; } r -= IIN;
.LBB0_901:
	s_andn2_saveexec_b64 s[26:27], s[26:27]
	s_cbranch_execz .LBB0_894
	s_mov_b32 s4, 0x8ca29c05
	v_mul_hi_i32 v7, v30, s4
	v_add_u32_e32 v7, v7, v30
	v_lshrrev_b32_e32 v8, 31, v7
	v_ashrrev_i32_e32 v7, 7, v7
	v_add_u32_e32 v7, v7, v8
	s_movk_i32 s4, 0xe2e0
	v_mul_lo_u32 v9, v7, s4
	v_add3_u32 v10, v1, v28, v9
	v_lshlrev_b32_e32 v8, 6, v7
	v_ashrrev_i32_e32 v11, 31, v10
	v_cmp_gt_i32_e32 vcc, s37, v10
	v_or_b32_e32 v14, v8, v21
	v_lshl_add_u64 v[10:11], v[10:11], 2, s[12:13]
	v_mov_b32_e32 v13, 0
	v_mov_b32_e32 v12, 0
	s_and_saveexec_b64 s[4:5], vcc
	s_cbranch_execz .LBB0_904
	v_mad_i64_i32 v[16:17], s[28:29], v14, s61, v[10:11]
	global_load_dword v12, v[16:17], off nt
.LBB0_904:
	s_or_b64 exec, exec, s[4:5]
	s_and_saveexec_b64 s[4:5], vcc
	s_cbranch_execz .LBB0_906
	v_or_b32_e32 v13, 2, v14
	v_mad_i64_i32 v[16:17], s[28:29], v13, s61, v[10:11]
	global_load_dword v13, v[16:17], off nt
.LBB0_906:
	s_or_b64 exec, exec, s[4:5]
	v_mov_b32_e32 v15, 0
	v_mov_b32_e32 v16, 0
	s_and_saveexec_b64 s[4:5], vcc
	s_cbranch_execz .LBB0_908
	v_or_b32_e32 v16, 4, v14
	v_mad_i64_i32 v[16:17], s[28:29], v16, s61, v[10:11]
	global_load_dword v16, v[16:17], off nt
.LBB0_908:
	s_or_b64 exec, exec, s[4:5]
	s_and_saveexec_b64 s[4:5], vcc
	s_cbranch_execz .LBB0_910
	v_or_b32_e32 v15, 6, v14
	v_mad_i64_i32 v[18:19], s[28:29], v15, s61, v[10:11]
	global_load_dword v15, v[18:19], off nt
.LBB0_910:
	s_or_b64 exec, exec, s[4:5]
	v_mov_b32_e32 v17, 0
	v_mov_b32_e32 v18, 0
	s_and_saveexec_b64 s[4:5], vcc
	s_cbranch_execz .LBB0_912
	v_or_b32_e32 v18, 8, v14
	v_mad_i64_i32 v[18:19], s[28:29], v18, s61, v[10:11]
	global_load_dword v18, v[18:19], off nt
.LBB0_912:
	s_or_b64 exec, exec, s[4:5]
	s_and_saveexec_b64 s[4:5], vcc
	s_cbranch_execz .LBB0_914
	v_or_b32_e32 v17, 10, v14
	v_mad_i64_i32 v[32:33], s[28:29], v17, s61, v[10:11]
	global_load_dword v17, v[32:33], off nt
.LBB0_914:
	s_or_b64 exec, exec, s[4:5]
	v_mov_b32_e32 v19, 0
	v_mov_b32_e32 v31, 0
	s_and_saveexec_b64 s[4:5], vcc
	s_cbranch_execz .LBB0_916
	v_or_b32_e32 v31, 12, v14
	v_mad_i64_i32 v[32:33], s[28:29], v31, s61, v[10:11]
	global_load_dword v31, v[32:33], off nt
.LBB0_916:
	s_or_b64 exec, exec, s[4:5]
	s_and_saveexec_b64 s[4:5], vcc
	s_cbranch_execz .LBB0_918
	v_or_b32_e32 v19, 14, v14
	v_mad_i64_i32 v[32:33], s[28:29], v19, s61, v[10:11]
	global_load_dword v19, v[32:33], off nt
.LBB0_918:
	s_or_b64 exec, exec, s[4:5]
	v_mov_b32_e32 v32, 0
	v_mov_b32_e32 v33, 0
	s_and_saveexec_b64 s[4:5], vcc
	s_cbranch_execz .LBB0_920
	v_or_b32_e32 v33, 16, v14
	v_mad_i64_i32 v[34:35], s[28:29], v33, s61, v[10:11]
	global_load_dword v33, v[34:35], off nt
.LBB0_920:
	s_or_b64 exec, exec, s[4:5]
	s_and_saveexec_b64 s[4:5], vcc
	s_cbranch_execz .LBB0_922
	v_or_b32_e32 v32, 18, v14
	v_mad_i64_i32 v[34:35], s[28:29], v32, s61, v[10:11]
	global_load_dword v32, v[34:35], off nt
.LBB0_922:
	s_or_b64 exec, exec, s[4:5]
	v_mov_b32_e32 v34, 0
	v_mov_b32_e32 v35, 0
	s_and_saveexec_b64 s[4:5], vcc
	s_cbranch_execz .LBB0_924
	v_or_b32_e32 v35, 20, v14
	v_mad_i64_i32 v[36:37], s[28:29], v35, s61, v[10:11]
	global_load_dword v35, v[36:37], off nt
.LBB0_924:
	s_or_b64 exec, exec, s[4:5]
	s_and_saveexec_b64 s[4:5], vcc
	s_cbranch_execz .LBB0_926
	v_or_b32_e32 v34, 22, v14
	v_mad_i64_i32 v[36:37], s[28:29], v34, s61, v[10:11]
	global_load_dword v34, v[36:37], off nt
.LBB0_926:
	s_or_b64 exec, exec, s[4:5]
	v_mov_b32_e32 v36, 0
	v_mov_b32_e32 v37, 0
	s_and_saveexec_b64 s[4:5], vcc
	s_cbranch_execz .LBB0_928
	v_or_b32_e32 v37, 24, v14
	v_mad_i64_i32 v[38:39], s[28:29], v37, s61, v[10:11]
	global_load_dword v37, v[38:39], off nt
.LBB0_928:
	s_or_b64 exec, exec, s[4:5]
	s_and_saveexec_b64 s[4:5], vcc
	s_cbranch_execz .LBB0_930
	v_or_b32_e32 v36, 26, v14
	v_mad_i64_i32 v[38:39], s[28:29], v36, s61, v[10:11]
	global_load_dword v36, v[38:39], off nt
.LBB0_930:
	s_or_b64 exec, exec, s[4:5]
	v_mov_b32_e32 v38, 0
	v_mov_b32_e32 v39, 0
	s_and_saveexec_b64 s[4:5], vcc
	s_cbranch_execz .LBB0_932
	v_or_b32_e32 v39, 28, v14
	v_mad_i64_i32 v[40:41], s[28:29], v39, s61, v[10:11]
	global_load_dword v39, v[40:41], off nt
; DI void conv_item(const float* W, int K, int N, bf16_t* WT, int mode, float* scr, int item, int lane) {
;     ...
; #pragma unroll
;     for (int i = 0; i < 32; ++i) { const int kk = 2 * i + (lane >> 5); wv[i] = okn ? W[(size_t)(k0 + kk) * N + nn] : 0.f; }
.LBB0_932:
	s_or_b64 exec, exec, s[4:5]
	s_and_saveexec_b64 s[4:5], vcc
	s_cbranch_execz .LBB0_934
	v_or_b32_e32 v38, 30, v14
	v_mad_i64_i32 v[40:41], s[28:29], v38, s61, v[10:11]
	global_load_dword v38, v[40:41], off nt
.LBB0_934:
	s_or_b64 exec, exec, s[4:5]
	v_mov_b32_e32 v40, 0
	v_mov_b32_e32 v41, 0
	s_and_saveexec_b64 s[4:5], vcc
	s_cbranch_execz .LBB0_936
	v_or_b32_e32 v41, 32, v14
	v_mad_i64_i32 v[42:43], s[28:29], v41, s61, v[10:11]
	global_load_dword v41, v[42:43], off nt
.LBB0_936:
	s_or_b64 exec, exec, s[4:5]
	s_and_saveexec_b64 s[4:5], vcc
	s_cbranch_execz .LBB0_938
	v_or_b32_e32 v40, 34, v14
	v_mad_i64_i32 v[42:43], s[28:29], v40, s61, v[10:11]
	global_load_dword v40, v[42:43], off nt
.LBB0_938:
	s_or_b64 exec, exec, s[4:5]
	v_mov_b32_e32 v42, 0
	v_mov_b32_e32 v43, 0
	s_and_saveexec_b64 s[4:5], vcc
	s_cbranch_execz .LBB0_940
	v_or_b32_e32 v43, 36, v14
	v_mad_i64_i32 v[44:45], s[28:29], v43, s61, v[10:11]
	global_load_dword v43, v[44:45], off nt
.LBB0_940:
	s_or_b64 exec, exec, s[4:5]
	s_and_saveexec_b64 s[4:5], vcc
	s_cbranch_execz .LBB0_942
	v_or_b32_e32 v42, 38, v14
	v_mad_i64_i32 v[44:45], s[28:29], v42, s61, v[10:11]
	global_load_dword v42, v[44:45], off nt
.LBB0_942:
	s_or_b64 exec, exec, s[4:5]
	v_mov_b32_e32 v44, 0
	v_mov_b32_e32 v45, 0
	s_and_saveexec_b64 s[4:5], vcc
	s_cbranch_execz .LBB0_944
	v_or_b32_e32 v45, 40, v14
	v_mad_i64_i32 v[46:47], s[28:29], v45, s61, v[10:11]
	global_load_dword v45, v[46:47], off nt
.LBB0_944:
	s_or_b64 exec, exec, s[4:5]
	s_and_saveexec_b64 s[4:5], vcc
	s_cbranch_execz .LBB0_946
	v_or_b32_e32 v44, 42, v14
	v_mad_i64_i32 v[46:47], s[28:29], v44, s61, v[10:11]
	global_load_dword v44, v[46:47], off nt
.LBB0_946:
	s_or_b64 exec, exec, s[4:5]
	v_mov_b32_e32 v46, 0
	v_mov_b32_e32 v47, 0
	s_and_saveexec_b64 s[4:5], vcc
	s_cbranch_execz .LBB0_948
	v_or_b32_e32 v47, 44, v14
	v_mad_i64_i32 v[48:49], s[28:29], v47, s61, v[10:11]
	global_load_dword v47, v[48:49], off nt
.LBB0_948:
	s_or_b64 exec, exec, s[4:5]
	s_and_saveexec_b64 s[4:5], vcc
	s_cbranch_execz .LBB0_950
	v_or_b32_e32 v46, 46, v14
	v_mad_i64_i32 v[48:49], s[28:29], v46, s61, v[10:11]
	global_load_dword v46, v[48:49], off nt
.LBB0_950:
	s_or_b64 exec, exec, s[4:5]
	v_mov_b32_e32 v48, 0
	v_mov_b32_e32 v49, 0
	s_and_saveexec_b64 s[4:5], vcc
	s_cbranch_execz .LBB0_952
	v_or_b32_e32 v49, 48, v14
	v_mad_i64_i32 v[50:51], s[28:29], v49, s61, v[10:11]
	global_load_dword v49, v[50:51], off nt
.LBB0_952:
	s_or_b64 exec, exec, s[4:5]
	s_and_saveexec_b64 s[4:5], vcc
	s_cbranch_execz .LBB0_954
	v_or_b32_e32 v48, 50, v14
	v_mad_i64_i32 v[50:51], s[28:29], v48, s61, v[10:11]
	global_load_dword v48, v[50:51], off nt
.LBB0_954:
	s_or_b64 exec, exec, s[4:5]
	v_mov_b32_e32 v51, 0
	v_mov_b32_e32 v52, 0
	s_and_saveexec_b64 s[4:5], vcc
	s_cbranch_execz .LBB0_956
	v_or_b32_e32 v50, 52, v14
	v_mad_i64_i32 v[52:53], s[28:29], v50, s61, v[10:11]
	global_load_dword v52, v[52:53], off nt
.LBB0_956:
	s_or_b64 exec, exec, s[4:5]
	s_and_saveexec_b64 s[4:5], vcc
	s_cbranch_execz .LBB0_958
	v_or_b32_e32 v50, 54, v14
	v_mad_i64_i32 v[50:51], s[28:29], v50, s61, v[10:11]
	global_load_dword v51, v[50:51], off nt
.LBB0_958:
	s_or_b64 exec, exec, s[4:5]
	v_mov_b32_e32 v53, 0
	v_mov_b32_e32 v54, 0
	s_and_saveexec_b64 s[4:5], vcc
	s_cbranch_execz .LBB0_960
	v_or_b32_e32 v50, 56, v14
	v_mad_i64_i32 v[54:55], s[28:29], v50, s61, v[10:11]
	global_load_dword v54, v[54:55], off nt
.LBB0_960:
	s_or_b64 exec, exec, s[4:5]
	s_and_saveexec_b64 s[4:5], vcc
	s_cbranch_execz .LBB0_962
	v_or_b32_e32 v50, 58, v14
	v_mad_i64_i32 v[56:57], s[28:29], v50, s61, v[10:11]
	global_load_dword v53, v[56:57], off nt
.LBB0_962:
	s_or_b64 exec, exec, s[4:5]
	v_mov_b32_e32 v55, 0
	v_mov_b32_e32 v56, 0
	s_and_saveexec_b64 s[4:5], vcc
	s_cbranch_execz .LBB0_964
	v_or_b32_e32 v50, 60, v14
	v_mad_i64_i32 v[56:57], s[28:29], v50, s61, v[10:11]
	global_load_dword v56, v[56:57], off nt
.LBB0_964:
	s_or_b64 exec, exec, s[4:5]
	s_and_saveexec_b64 s[4:5], vcc
	s_cbranch_execz .LBB0_966
	v_or_b32_e32 v14, 62, v14
	v_mad_i64_i32 v[10:11], s[28:29], v14, s61, v[10:11]
	global_load_dword v55, v[10:11], off nt
